# bundle + waves 0-3 skip the Wp product (waves 4-7, same value tiles, compute their two tiles) and start the block inverses at once; split 17:15
# speedup vs baseline: 1.1050x; 1.0044x over previous
.LBB0_385:
	s_waitcnt lgkmcnt(0)
	s_barrier
	s_waitcnt lgkmcnt(0)
	v_readfirstlane_b32 s26, v0
	s_lshr_b32 s26, s26, 6
	s_cmp_lt_u32 s26, 4
	s_cbranch_scc1 .Lp5_skip
	ds_read_b128 v[66:69], v224 offset:16384
	ds_read_b128 v[70:73], v225
	v_cndmask_b32_e64 v26, 0, 1, s[4:5]
	v_cmp_ne_u32_e64 s[52:53], 1, v26
	s_waitcnt lgkmcnt(0)
	v_mfma_f32_16x16x32_bf16 v[66:69], v[66:69], v[70:73], 0
	s_andn2_b64 vcc, exec, s[4:5]
	s_cbranch_vccnz .LBB0_387
	ds_read_b128 v[70:73], v224 offset:16448
	ds_read_b128 v[74:77], v225 offset:64
	s_waitcnt lgkmcnt(0)
	v_mfma_f32_16x16x32_bf16 v[66:69], v[70:73], v[74:77], v[66:69]

.LBB0_389:
	s_andn2_b64 vcc, exec, s[8:9]
	s_nop 6
	ds_write2_b32 v26, v66, v67 offset0:16 offset1:88
	ds_write2_b32 v26, v68, v69 offset0:160 offset1:232
	v_add_u32_e32 v27, 0xffffec00, v224
	v_add_u32_e32 v28, 0xffffdc00, v26
	ds_read_b128 v[66:69], v27 offset:16384
	ds_read_b128 v[70:73], v225
	s_waitcnt lgkmcnt(0)
	v_mfma_f32_16x16x32_bf16 v[66:69], v[66:69], v[70:73], 0
	s_nop 7
	ds_write2_b32 v28, v66, v67 offset1:72
	ds_write2_b32 v28, v68, v69 offset0:144 offset1:216
	ds_read_b128 v[66:69], v27 offset:16384
	ds_read_b128 v[70:73], v226
	s_waitcnt lgkmcnt(0)
	v_mfma_f32_16x16x32_bf16 v[66:69], v[66:69], v[70:73], 0
	s_nop 7
	ds_write2_b32 v28, v66, v67 offset0:16 offset1:88
	ds_write2_b32 v28, v68, v69 offset0:160 offset1:232
.Lp5_skip:
	v_readfirstlane_b32 s26, v0
	s_lshr_b32 s26, s26, 6
	s_cmp_gt_u32 s26, 3
	s_cbranch_scc1 .LBB0_391
	s_mul_i32 s27, s26, 0xa20
	v_and_b32_e32 v28, 63, v0
	v_and_b32_e32 v166, 15, v28
	v_lshrrev_b32_e32 v173, 4, v28
	v_mul_u32_u24_e32 v186, 0xa0, v166
	v_lshl_add_u32 v186, v173, 3, v186
	v_add_u32_e32 v186, s27, v186
	ds_read_b64 v[26:27], v186
	v_lshrrev_b32_e32 v188, 2, v166
	v_lshl_add_u32 v188, v173, 2, v188
	v_mul_u32_u24_e32 v188, 0xa0, v188
	v_and_b32_e32 v28, 3, v166
	v_lshl_add_u32 v188, v28, 3, v188
	v_add_u32_e32 v188, s27, v188
	ds_read_b64_tr_b16 v[110:111], v188
	s_lshl_b32 s27, s26, 10
	v_lshlrev_b32_e32 v186, 6, v166
	v_lshl_add_u32 v186, v173, 4, v186
	v_add_u32_e32 v186, s27, v186
	v_add_u32_e32 v186, 0x2800, v186
	v_lshlrev_b32_e32 v28, 2, v173
	v_sub_u32_e32 v28, v166, v28
	v_med3_i32 v66, v28, 0, 4
	v_lshlrev_b32_e64 v66, v66, 1
	v_add_u32_e32 v66, -1, v66
	v_lshlrev_b32_e64 v67, v28, 1
	v_and_b32_e32 v67, 15, v67
	v_bfe_i32 v72, v66, 0, 1
	v_bfe_i32 v73, v66, 1, 1
	v_lshrrev_b32_e32 v72, 16, v72
	v_and_b32_e32 v73, 0xffff0000, v73
	v_or_b32_e32 v68, v72, v73
	v_bfe_i32 v72, v66, 2, 1
	v_bfe_i32 v73, v66, 3, 1
	v_lshrrev_b32_e32 v72, 16, v72
	v_and_b32_e32 v73, 0xffff0000, v73
	v_or_b32_e32 v69, v72, v73
	v_bfe_i32 v72, v67, 0, 1
	v_bfe_i32 v73, v67, 1, 1
	v_lshrrev_b32_e32 v72, 16, v72
	v_and_b32_e32 v73, 0xffff0000, v73
	v_or_b32_e32 v70, v72, v73
	v_bfe_i32 v72, v67, 2, 1
	v_bfe_i32 v73, v67, 3, 1
	v_lshrrev_b32_e32 v72, 16, v72
	v_and_b32_e32 v73, 0xffff0000, v73
	v_or_b32_e32 v71, v72, v73
	v_or_b32_e32 v74, v68, v70
	v_or_b32_e32 v75, v69, v71
	v_not_b32_e32 v74, v74
	v_not_b32_e32 v75, v75
	v_and_b32_e32 v166, 0x3f803f80, v70
	v_and_b32_e32 v173, 0x3f803f80, v71
	v_and_b32_e32 v76, 0x80008000, v68
	v_and_b32_e32 v77, 0x80008000, v69
	s_waitcnt lgkmcnt(1)
	v_and_b32_e32 v26, v26, v68
	v_and_b32_e32 v27, v27, v69
	s_waitcnt lgkmcnt(0)
	v_and_b32_e32 v110, v110, v74
	v_and_b32_e32 v111, v111, v75
	v_xor_b32_e32 v184, v26, v76
	v_xor_b32_e32 v185, v27, v77
	v_or_b32_e32 v184, v184, v166
	v_or_b32_e32 v185, v185, v173
	v_mfma_f32_16x16x16_bf16 v[66:69], v[26:27], v[110:111], 0
	v_mfma_f32_16x16x16_bf16 v[70:73], v[110:111], v[26:27], 0
	s_nop 7
	v_cvt_pk_bf16_f32 v168, v66, v67
	v_cvt_pk_bf16_f32 v169, v68, v69
	v_cvt_pk_bf16_f32 v170, v70, v71
	v_cvt_pk_bf16_f32 v171, v72, v73
	v_or_b32_e32 v26, v168, v166
	v_or_b32_e32 v27, v169, v173
	s_nop 1
	v_mfma_f32_16x16x16_bf16 v[74:77], v[26:27], v[184:185], 0
	v_mfma_f32_16x16x16_bf16 v[66:69], v[170:171], v[168:169], 0
	v_mfma_f32_16x16x16_bf16 v[70:73], v[168:169], v[170:171], 0
	s_nop 6
	v_cvt_pk_bf16_f32 v26, v74, v75
	v_cvt_pk_bf16_f32 v27, v76, v77
	v_cvt_pk_bf16_f32 v110, v66, v67
	v_cvt_pk_bf16_f32 v111, v68, v69
	v_cvt_pk_bf16_f32 v184, v70, v71
	v_cvt_pk_bf16_f32 v185, v72, v73
	s_nop 1
	v_mfma_f32_16x16x16_bf16 v[66:69], v[184:185], v[110:111], 0
	v_or_b32_e32 v184, v184, v166
	v_or_b32_e32 v185, v185, v173
	s_nop 6
	v_cvt_pk_bf16_f32 v110, v66, v67
	v_cvt_pk_bf16_f32 v111, v68, v69
	v_or_b32_e32 v110, v110, v166
	v_or_b32_e32 v111, v111, v173
	s_nop 1
	v_mfma_f32_16x16x16_bf16 v[70:73], v[184:185], v[110:111], 0
	s_nop 7
	v_cvt_pk_bf16_f32 v168, v70, v71
	v_cvt_pk_bf16_f32 v169, v72, v73
	s_nop 1
	v_mfma_f32_16x16x16_bf16 v[66:69], v[168:169], v[26:27], 0
	s_nop 7
	ds_write_b128 v186, v[66:69]
	s_branch .LBB0_391
